# grid barrier (in-loop instances): all waiters poll the cross-XCD arrival counter until it reaches (round+1)*nx; the last leader no longer publishes a release generation
# baseline (speedup 1.0000x reference)
.LBB0_447:
	s_or_b64 exec, exec, s[12:13]
	v_cvt_f32_u32_e32 v4, v2
	s_waitcnt vmcnt(0)
	v_readfirstlane_b32 s3, v3
	v_sub_u32_e32 v3, 0, v2
	v_rcp_iflag_f32_e32 v4, v4
	v_add_u32_e32 v5, s3, v1
	v_mul_f32_e32 v4, 0x4f7ffffe, v4
	v_cvt_u32_f32_e32 v4, v4
	v_mul_lo_u32 v1, v3, v4
	v_mul_hi_u32 v1, v4, v1
	v_add_u32_e32 v1, v4, v1
	v_mul_hi_u32 v1, v5, v1
	v_mul_lo_u32 v3, v1, v2
	v_sub_u32_e32 v3, v5, v3
	v_add_u32_e32 v4, 1, v1
	v_cmp_ge_u32_e32 vcc, v3, v2
	s_nop 1
	v_cndmask_b32_e32 v1, v1, v4, vcc
	v_sub_u32_e32 v4, v3, v2
	v_cndmask_b32_e32 v3, v3, v4, vcc
	v_add_u32_e32 v4, 1, v1
	v_cmp_ge_u32_e32 vcc, v3, v2
	v_add_u32_e32 v3, 1, v5
	s_nop 0
	v_cndmask_b32_e32 v1, v1, v4, vcc
	v_mul_lo_u32 v4, v2, v1
	v_add_u32_e32 v2, v4, v2
	v_cmp_ne_u32_e32 vcc, v3, v2
	s_and_saveexec_b64 s[10:11], vcc
	s_xor_b64 s[10:11], exec, s[10:11]
	s_cbranch_execz .LBB0_461
	s_waitcnt lgkmcnt(0)
	v_add_u32_e32 v1, 1, v1
	v_mul_lo_u32 v1, v1, v0
	s_add_u32 s14, s6, 0x3400
	s_addc_u32 s15, s7, 0
	global_load_dword v0, v145, s[14:15] sc1
	s_waitcnt vmcnt(0)
	v_cmp_lt_u32_e32 vcc, v0, v1
	s_and_saveexec_b64 s[12:13], vcc
	s_cbranch_execz .LBB0_460
	s_mov_b32 s3, 1
	s_mov_b64 s[16:17], 0
	s_branch .LBB0_451

.LBB0_455:
	global_load_dword v0, v145, s[14:15] sc1
	s_add_i32 s3, s3, 1
	s_mov_b64 s[22:23], -1
	s_waitcnt vmcnt(0)
	v_cmp_ge_u32_e32 vcc, v0, v1
	s_orn2_b64 s[20:21], vcc, exec
	s_branch .LBB0_450

.LBB0_464:
	s_or_b64 exec, exec, s[12:13]
	s_waitcnt vmcnt(0)
	v_readfirstlane_b32 s3, v2
	v_cvt_f32_u32_e32 v2, v0
	v_sub_u32_e32 v3, 0, v0
	v_add_u32_e32 v1, s3, v1
	s_add_u32 s10, s6, 0x3400
	v_rcp_iflag_f32_e32 v2, v2
	s_addc_u32 s11, s7, 0
	s_mov_b64 s[14:15], 0
	v_mul_f32_e32 v2, 0x4f7ffffe, v2
	v_cvt_u32_f32_e32 v2, v2
	v_mul_lo_u32 v3, v3, v2
	v_mul_hi_u32 v3, v2, v3
	v_add_u32_e32 v2, v2, v3
	v_mul_hi_u32 v2, v1, v2
	v_mul_lo_u32 v3, v2, v0
	v_sub_u32_e32 v3, v1, v3
	v_cmp_ge_u32_e32 vcc, v3, v0
	v_add_u32_e32 v4, 1, v2
	v_add_u32_e32 v1, 1, v1
	v_cndmask_b32_e32 v2, v2, v4, vcc
	v_sub_u32_e32 v4, v3, v0
	v_cndmask_b32_e32 v3, v3, v4, vcc
	v_cmp_ge_u32_e32 vcc, v3, v0
	v_add_u32_e32 v3, 1, v2
	s_nop 0
	v_cndmask_b32_e32 v2, v2, v3, vcc
	v_mul_lo_u32 v3, v0, v2
	v_add_u32_e32 v0, v3, v0
	v_cmp_ne_u32_e32 vcc, v1, v0
	v_mov_b32_e32 v2, v0
	v_mov_b64_e32 v[0:1], s[10:11]
	s_and_saveexec_b64 s[12:13], vcc
	s_cbranch_execz .LBB0_476
	global_load_dword v0, v145, s[10:11] sc1
	s_mov_b64 s[18:19], 0
	s_waitcnt vmcnt(0)
	v_cmp_lt_u32_e32 vcc, v0, v2
	s_and_saveexec_b64 s[16:17], vcc
	s_cbranch_execz .LBB0_475
	s_add_u32 s14, s6, 0x200
	s_addc_u32 s15, s7, 0
	s_mov_b32 s3, 1
	s_mov_b64 s[6:7], 0
	s_branch .LBB0_468

.LBB0_472:
	global_load_dword v0, v145, s[10:11] sc1
	s_add_i32 s3, s3, 1
	s_mov_b64 s[22:23], -1
	s_waitcnt vmcnt(0)
	v_cmp_ge_u32_e32 vcc, v0, v2
	s_orn2_b64 s[20:21], vcc, exec
	s_branch .LBB0_467

.LBB0_1400:
	s_or_b64 exec, exec, s[14:15]
	v_cvt_f32_u32_e32 v4, v2
	s_waitcnt vmcnt(0)
	v_readfirstlane_b32 s3, v3
	v_sub_u32_e32 v3, 0, v2
	v_rcp_iflag_f32_e32 v4, v4
	v_add_u32_e32 v5, s3, v1
	v_mul_f32_e32 v4, 0x4f7ffffe, v4
	v_cvt_u32_f32_e32 v4, v4
	v_mul_lo_u32 v1, v3, v4
	v_mul_hi_u32 v1, v4, v1
	v_add_u32_e32 v1, v4, v1
	v_mul_hi_u32 v1, v5, v1
	v_mul_lo_u32 v3, v1, v2
	v_sub_u32_e32 v3, v5, v3
	v_add_u32_e32 v4, 1, v1
	v_cmp_ge_u32_e32 vcc, v3, v2
	s_nop 1
	v_cndmask_b32_e32 v1, v1, v4, vcc
	v_sub_u32_e32 v4, v3, v2
	v_cndmask_b32_e32 v3, v3, v4, vcc
	v_add_u32_e32 v4, 1, v1
	v_cmp_ge_u32_e32 vcc, v3, v2
	v_add_u32_e32 v3, 1, v5
	s_nop 0
	v_cndmask_b32_e32 v1, v1, v4, vcc
	v_mul_lo_u32 v4, v2, v1
	v_add_u32_e32 v2, v4, v2
	v_cmp_ne_u32_e32 vcc, v3, v2
	s_and_saveexec_b64 s[12:13], vcc
	s_xor_b64 s[12:13], exec, s[12:13]
	s_cbranch_execz .LBB0_1414
	s_waitcnt lgkmcnt(0)
	v_add_u32_e32 v1, 1, v1
	v_mul_lo_u32 v1, v1, v0
	s_add_u32 s16, s8, 0x3400
	s_addc_u32 s17, s9, 0
	global_load_dword v0, v145, s[16:17] sc1
	s_waitcnt vmcnt(0)
	v_cmp_lt_u32_e32 vcc, v0, v1
	s_and_saveexec_b64 s[14:15], vcc
	s_cbranch_execz .LBB0_1413
	s_mov_b32 s3, 1
	s_mov_b64 s[18:19], 0
	s_branch .LBB0_1404

.LBB0_1408:
	global_load_dword v0, v145, s[16:17] sc1
	s_add_i32 s3, s3, 1
	s_mov_b64 s[24:25], -1
	s_waitcnt vmcnt(0)
	v_cmp_ge_u32_e32 vcc, v0, v1
	s_orn2_b64 s[22:23], vcc, exec
	s_branch .LBB0_1403

.LBB0_1417:
	s_or_b64 exec, exec, s[14:15]
	s_waitcnt vmcnt(0)
	v_readfirstlane_b32 s3, v2
	v_cvt_f32_u32_e32 v2, v0
	v_sub_u32_e32 v3, 0, v0
	v_add_u32_e32 v1, s3, v1
	s_add_u32 s12, s8, 0x3400
	v_rcp_iflag_f32_e32 v2, v2
	s_addc_u32 s13, s9, 0
	s_mov_b64 s[16:17], 0
	v_mul_f32_e32 v2, 0x4f7ffffe, v2
	v_cvt_u32_f32_e32 v2, v2
	v_mul_lo_u32 v3, v3, v2
	v_mul_hi_u32 v3, v2, v3
	v_add_u32_e32 v2, v2, v3
	v_mul_hi_u32 v2, v1, v2
	v_mul_lo_u32 v3, v2, v0
	v_sub_u32_e32 v3, v1, v3
	v_cmp_ge_u32_e32 vcc, v3, v0
	v_add_u32_e32 v4, 1, v2
	v_add_u32_e32 v1, 1, v1
	v_cndmask_b32_e32 v2, v2, v4, vcc
	v_sub_u32_e32 v4, v3, v0
	v_cndmask_b32_e32 v3, v3, v4, vcc
	v_cmp_ge_u32_e32 vcc, v3, v0
	v_add_u32_e32 v3, 1, v2
	s_nop 0
	v_cndmask_b32_e32 v2, v2, v3, vcc
	v_mul_lo_u32 v3, v0, v2
	v_add_u32_e32 v0, v3, v0
	v_cmp_ne_u32_e32 vcc, v1, v0
	v_mov_b32_e32 v2, v0
	v_mov_b64_e32 v[0:1], s[12:13]
	s_and_saveexec_b64 s[14:15], vcc
	s_cbranch_execz .LBB0_1429
	global_load_dword v0, v145, s[12:13] sc1
	s_mov_b64 s[20:21], 0
	s_waitcnt vmcnt(0)
	v_cmp_lt_u32_e32 vcc, v0, v2
	s_and_saveexec_b64 s[18:19], vcc
	s_cbranch_execz .LBB0_1428
	s_add_u32 s16, s8, 0x200
	s_addc_u32 s17, s9, 0
	s_mov_b32 s3, 1
	s_mov_b64 s[8:9], 0
	s_branch .LBB0_1421

.LBB0_1425:
	global_load_dword v0, v145, s[12:13] sc1
	s_add_i32 s3, s3, 1
	s_mov_b64 s[24:25], -1
	s_waitcnt vmcnt(0)
	v_cmp_ge_u32_e32 vcc, v0, v2
	s_orn2_b64 s[22:23], vcc, exec
	s_branch .LBB0_1420
